# grid barrier: XCD leader publishes the per-XCD generation before its own acquire invalidate
# baseline (speedup 1.0000x reference)
; __device__ __forceinline__ unsigned xb_ld(unsigned* p)              { return __hip_atomic_load(p, __ATOMIC_RELAXED, __HIP_MEMORY_SCOPE_AGENT); }
; __device__ __forceinline__ unsigned xb_add(unsigned* p, unsigned v) { return __hip_atomic_fetch_add(p, v, __ATOMIC_RELAXED, __HIP_MEMORY_SCOPE_AGENT); }
; #define XB_SPIN(cond, bar) do { unsigned _sp = 0; while (cond) { __builtin_amdgcn_s_sleep(1); \
;     if ((++_sp & 255u) == 0u) { if (xb_ld(&(bar)[XB_TMO])) break; if (_sp > XB_SPIN_CAP) { atomicAdd(&(bar)[XB_TMO], 1u); break; } } } } while (0)
; __device__ __forceinline__ void xcd_barrier(const XcdBarrier& b) {
;     ...
;             const unsigned og = xb_add(&bar[XB_TOP], 1u);
;             const unsigned tg = og / nx;
;             if (og + 1u == (tg + 1u) * nx) xb_add(&bar[XB_TOPGEN], 1u);
;             else XB_SPIN(xb_ld(&bar[XB_TOPGEN]) == tg, bar);
;             __builtin_amdgcn_fence(__ATOMIC_ACQUIRE, "agent");
;             xb_add(&bar[XB_XGEN(b.x)], 1u);
;             asm volatile("s_waitcnt vmcnt(0)" ::: "memory");
;         } else {
;             XB_SPIN(xb_ld(&bar[XB_XGEN(b.x)]) == gen, bar);
;             __builtin_amdgcn_fence(__ATOMIC_ACQUIRE, "agent");
;             asm volatile("s_waitcnt vmcnt(0)" ::: "memory");
.LBB0_678:
	s_or_b64 exec, exec, s[4:5]
	s_mov_b64 s[4:5], exec
	v_mbcnt_lo_u32_b32 v0, s4, 0
	v_mbcnt_hi_u32_b32 v0, s5, v0
	v_cmp_eq_u32_e32 vcc, 0, v0
	s_waitcnt vmcnt(0)
	s_and_saveexec_b64 s[6:7], vcc
	s_cbranch_execz .LBB0_680
	s_bcnt1_i32_b64 s2, s[4:5]
	v_mov_b32_e32 v0, s2
	v_readlane_b32 s2, v253, 12
	v_readlane_b32 s3, v253, 13
	s_nop 4
	global_atomic_add v1, v0, s[2:3]
.LBB0_680:
	s_or_b64 exec, exec, s[6:7]
	buffer_inv sc1
	s_waitcnt vmcnt(0)
